# remove conservative vmcnt(0) at GEMM unit start (acc zeroing) on top of mfmasched
# baseline (speedup 1.0000x reference)
; template <class Epi, class Sched, bool ALIGN_EPI = true>
; __device__ __forceinline__ void gemm_phase(PG8_LAS unsigned char* lds, const Gemm g, const Sched& S, const Epi& E, const int tid) {
;     ...
;         const char* nA = has_next ? (const char*)g.A + (size_t)nxt.pm * tstepA + (size_t)nxt.grp * g.gsA + (size_t)nxt.kt0 * kstep : cA;
;         const char* nB = has_next ? (const char*)g.Bt + (size_t)nxt.pn * tstepB + (size_t)nxt.grp * g.gsB + (size_t)nxt.kt0 * kstep : cB;
;     ...
; #pragma unroll
;         for (int a = 0; a < 2; ++a)
; #pragma unroll
;             for (int b = 0; b < 2; ++b)
; #pragma unroll
;                 for (int m = 0; m < 4; ++m)
; #pragma unroll
;                     for (int n = 0; n < 2; ++n) acc[a][b][m][n] = (f32x4){0.f, 0.f, 0.f, 0.f};
;         cur = nxt; cA = nA; cB = nB; ++ui;
.LBB0_425:
	s_ashr_i32 s53, s52, 31
	s_lshl_b64 s[8:9], s[52:53], 20
	s_add_u32 s1, s19, s8
	s_addc_u32 s5, s64, s9
	s_ashr_i32 s55, s54, 31
	s_lshl_b64 s[8:9], s[54:55], 10
	s_add_u32 s58, s1, s8
	s_addc_u32 s59, s5, s9
	s_and_b64 s[8:9], s[38:39], exec
	s_cselect_b32 s1, s59, s63
	s_cselect_b32 s5, s58, s62
	s_ashr_i32 s57, s56, 31
	s_lshl_b64 s[8:9], s[56:57], 18
	s_add_u32 s12, s65, s8
	s_addc_u32 s13, s66, s9
	s_lshl_b64 s[8:9], s[54:55], 19
	s_add_u32 s60, s12, s8
	s_addc_u32 s61, s13, s9
	s_and_b64 s[8:9], s[38:39], exec
	s_cselect_b32 s8, s61, s23
	s_cselect_b32 s9, s60, s22
	s_add_u32 s12, s62, 0x80080
	s_addc_u32 s13, s63, 0
	s_add_u32 s20, s22, 0x100
	v_mov_b32_e32 v4, 0
	s_addc_u32 s21, s23, 0
	s_mov_b32 s53, -2
	v_mov_b32_e32 v5, v4
	v_mov_b32_e32 v6, v4
	v_mov_b32_e32 v7, v4
	v_mov_b32_e32 v8, v4
	v_mov_b32_e32 v9, v4
	v_mov_b32_e32 v10, v4
	v_mov_b32_e32 v11, v4
	v_mov_b32_e32 v20, v4
	v_mov_b32_e32 v21, v4
	v_mov_b32_e32 v22, v4
	v_mov_b32_e32 v23, v4
	v_mov_b32_e32 v24, v4
	v_mov_b32_e32 v25, v4
	v_mov_b32_e32 v26, v4
	v_mov_b32_e32 v27, v4
	v_mov_b32_e32 v36, v4
	v_mov_b32_e32 v37, v4
	v_mov_b32_e32 v38, v4
	v_mov_b32_e32 v39, v4
	v_mov_b32_e32 v40, v4
	v_mov_b32_e32 v41, v4
	v_mov_b32_e32 v42, v4
	v_mov_b32_e32 v43, v4
	v_mov_b32_e32 v52, v4
	v_mov_b32_e32 v53, v4
	v_mov_b32_e32 v54, v4
	v_mov_b32_e32 v55, v4
	v_mov_b32_e32 v56, v4
	v_mov_b32_e32 v57, v4
	v_mov_b32_e32 v58, v4
	v_mov_b32_e32 v59, v4
	v_mov_b32_e32 v12, v4
	v_mov_b32_e32 v13, v4
	v_mov_b32_e32 v14, v4
	v_mov_b32_e32 v15, v4
	v_mov_b32_e32 v16, v4
	v_mov_b32_e32 v17, v4
	v_mov_b32_e32 v18, v4
	v_mov_b32_e32 v19, v4
	v_mov_b32_e32 v28, v4
	v_mov_b32_e32 v29, v4
	v_mov_b32_e32 v30, v4
	v_mov_b32_e32 v31, v4
	v_mov_b32_e32 v32, v4
	v_mov_b32_e32 v33, v4
	v_mov_b32_e32 v34, v4
	v_mov_b32_e32 v35, v4
	v_mov_b32_e32 v44, v4
	v_mov_b32_e32 v45, v4
	v_mov_b32_e32 v46, v4
	v_mov_b32_e32 v47, v4
	v_mov_b32_e32 v48, v4
	v_mov_b32_e32 v49, v4
	v_mov_b32_e32 v50, v4
	v_mov_b32_e32 v51, v4
	v_mov_b32_e32 v76, v4
	v_mov_b32_e32 v77, v4
	v_mov_b32_e32 v78, v4
	v_mov_b32_e32 v79, v4
	v_mov_b32_e32 v80, v4
	v_mov_b32_e32 v81, v4
	v_mov_b32_e32 v82, v4
	v_mov_b32_e32 v83, v4
	v_mov_b32_e32 v84, v4
	v_mov_b32_e32 v85, v4
	v_mov_b32_e32 v86, v4
	v_mov_b32_e32 v87, v4
	v_mov_b32_e32 v88, v4
	v_mov_b32_e32 v89, v4
	v_mov_b32_e32 v90, v4
	v_mov_b32_e32 v91, v4
	v_mov_b32_e32 v104, v4
	v_mov_b32_e32 v105, v4
	v_mov_b32_e32 v106, v4
	v_mov_b32_e32 v107, v4
	v_mov_b32_e32 v108, v4
	v_mov_b32_e32 v109, v4
	v_mov_b32_e32 v110, v4
	v_mov_b32_e32 v111, v4
	v_mov_b32_e32 v128, v4
	v_mov_b32_e32 v129, v4
	v_mov_b32_e32 v130, v4
	v_mov_b32_e32 v131, v4
	v_mov_b32_e32 v132, v4
	v_mov_b32_e32 v133, v4
	v_mov_b32_e32 v134, v4
	v_mov_b32_e32 v135, v4
	v_mov_b32_e32 v160, v4
	v_mov_b32_e32 v161, v4
	v_mov_b32_e32 v162, v4
	v_mov_b32_e32 v163, v4
	v_mov_b32_e32 v164, v4
	v_mov_b32_e32 v165, v4
	v_mov_b32_e32 v166, v4
	v_mov_b32_e32 v167, v4
	v_mov_b32_e32 v92, v4
	v_mov_b32_e32 v93, v4
	v_mov_b32_e32 v94, v4
	v_mov_b32_e32 v95, v4
	v_mov_b32_e32 v96, v4
	v_mov_b32_e32 v97, v4
	v_mov_b32_e32 v98, v4
	v_mov_b32_e32 v99, v4
	v_mov_b32_e32 v120, v4
	v_mov_b32_e32 v121, v4
	v_mov_b32_e32 v122, v4
	v_mov_b32_e32 v123, v4
	v_mov_b32_e32 v124, v4
	v_mov_b32_e32 v125, v4
	v_mov_b32_e32 v126, v4
	v_mov_b32_e32 v127, v4
	v_mov_b32_e32 v144, v4
	v_mov_b32_e32 v145, v4
	v_mov_b32_e32 v146, v4
	v_mov_b32_e32 v147, v4
	v_mov_b32_e32 v148, v4
	v_mov_b32_e32 v149, v4
	v_mov_b32_e32 v150, v4
	v_mov_b32_e32 v151, v4
	v_mov_b32_e32 v176, v4
	v_mov_b32_e32 v177, v4
	v_mov_b32_e32 v178, v4
	v_mov_b32_e32 v179, v4
	v_mov_b32_e32 v180, v4
	v_mov_b32_e32 v181, v4
	v_mov_b32_e32 v182, v4
	v_mov_b32_e32 v183, v4

; template <class Epi, class Sched, bool ALIGN_EPI = true>
; __device__ __forceinline__ void gemm_phase(PG8_LAS unsigned char* lds, const Gemm g, const Sched& S, const Epi& E, const int tid) {
;     ...
; #pragma unroll
;         for (int a = 0; a < 2; ++a)
; #pragma unroll
;             for (int b = 0; b < 2; ++b)
; #pragma unroll
;                 for (int m = 0; m < 4; ++m)
; #pragma unroll
;                     for (int n = 0; n < 2; ++n) acc[a][b][m][n] = (f32x4){0.f, 0.f, 0.f, 0.f};
;         cur = nxt; cA = nA; cB = nB; ++ui;
.LBB0_1086:
	s_add_i32 s1, s9, -2
	s_add_u32 s12, s12, 0x80080
	s_addc_u32 s13, s13, 0
	s_add_u32 s20, s22, 0x100
	v_mov_b32_e32 v4, 0
	s_addc_u32 s21, s23, 0
	s_mov_b32 s22, 0
	v_mov_b32_e32 v5, v4
	v_mov_b32_e32 v6, v4
	v_mov_b32_e32 v7, v4
	v_mov_b32_e32 v8, v4
	v_mov_b32_e32 v9, v4
	v_mov_b32_e32 v10, v4
	v_mov_b32_e32 v11, v4
	v_mov_b32_e32 v20, v4
	v_mov_b32_e32 v21, v4
	v_mov_b32_e32 v22, v4
	v_mov_b32_e32 v23, v4
	v_mov_b32_e32 v24, v4
	v_mov_b32_e32 v25, v4
	v_mov_b32_e32 v26, v4
	v_mov_b32_e32 v27, v4
	v_mov_b32_e32 v36, v4
	v_mov_b32_e32 v37, v4
	v_mov_b32_e32 v38, v4
	v_mov_b32_e32 v39, v4
	v_mov_b32_e32 v40, v4
	v_mov_b32_e32 v41, v4
	v_mov_b32_e32 v42, v4
	v_mov_b32_e32 v43, v4
	v_mov_b32_e32 v52, v4
	v_mov_b32_e32 v53, v4
	v_mov_b32_e32 v54, v4
	v_mov_b32_e32 v55, v4
	v_mov_b32_e32 v60, v4
	v_mov_b32_e32 v61, v4
	v_mov_b32_e32 v62, v4
	v_mov_b32_e32 v63, v4
	v_mov_b32_e32 v12, v4
	v_mov_b32_e32 v13, v4
	v_mov_b32_e32 v14, v4
	v_mov_b32_e32 v15, v4
	v_mov_b32_e32 v16, v4
	v_mov_b32_e32 v17, v4
	v_mov_b32_e32 v18, v4
	v_mov_b32_e32 v19, v4
	v_mov_b32_e32 v28, v4
	v_mov_b32_e32 v29, v4
	v_mov_b32_e32 v30, v4
	v_mov_b32_e32 v31, v4
	v_mov_b32_e32 v32, v4
	v_mov_b32_e32 v33, v4
	v_mov_b32_e32 v34, v4
	v_mov_b32_e32 v35, v4
	v_mov_b32_e32 v44, v4
	v_mov_b32_e32 v45, v4
	v_mov_b32_e32 v46, v4
	v_mov_b32_e32 v47, v4
	v_mov_b32_e32 v48, v4
	v_mov_b32_e32 v49, v4
	v_mov_b32_e32 v50, v4
	v_mov_b32_e32 v51, v4
	v_mov_b32_e32 v76, v4
	v_mov_b32_e32 v77, v4
	v_mov_b32_e32 v78, v4
	v_mov_b32_e32 v79, v4
	v_mov_b32_e32 v80, v4
	v_mov_b32_e32 v81, v4
	v_mov_b32_e32 v82, v4
	v_mov_b32_e32 v83, v4
	v_mov_b32_e32 v84, v4
	v_mov_b32_e32 v85, v4
	v_mov_b32_e32 v86, v4
	v_mov_b32_e32 v87, v4
	v_mov_b32_e32 v88, v4
	v_mov_b32_e32 v89, v4
	v_mov_b32_e32 v90, v4
	v_mov_b32_e32 v91, v4
	v_mov_b32_e32 v108, v4
	v_mov_b32_e32 v109, v4
	v_mov_b32_e32 v110, v4
	v_mov_b32_e32 v111, v4
	v_mov_b32_e32 v112, v4
	v_mov_b32_e32 v113, v4
	v_mov_b32_e32 v114, v4
	v_mov_b32_e32 v115, v4
	v_mov_b32_e32 v132, v4
	v_mov_b32_e32 v133, v4
	v_mov_b32_e32 v134, v4
	v_mov_b32_e32 v135, v4
	v_mov_b32_e32 v136, v4
	v_mov_b32_e32 v137, v4
	v_mov_b32_e32 v138, v4
	v_mov_b32_e32 v139, v4
	v_mov_b32_e32 v164, v4
	v_mov_b32_e32 v165, v4
	v_mov_b32_e32 v166, v4
	v_mov_b32_e32 v167, v4
	v_mov_b32_e32 v168, v4
	v_mov_b32_e32 v169, v4
	v_mov_b32_e32 v170, v4
	v_mov_b32_e32 v171, v4
	v_mov_b32_e32 v96, v4
	v_mov_b32_e32 v97, v4
	v_mov_b32_e32 v98, v4
	v_mov_b32_e32 v99, v4
	v_mov_b32_e32 v100, v4
	v_mov_b32_e32 v101, v4
	v_mov_b32_e32 v102, v4
	v_mov_b32_e32 v103, v4
	v_mov_b32_e32 v120, v4
	v_mov_b32_e32 v121, v4
	v_mov_b32_e32 v122, v4
	v_mov_b32_e32 v123, v4
	v_mov_b32_e32 v124, v4
	v_mov_b32_e32 v125, v4
	v_mov_b32_e32 v126, v4
	v_mov_b32_e32 v127, v4
	v_mov_b32_e32 v144, v4
	v_mov_b32_e32 v145, v4
	v_mov_b32_e32 v146, v4
	v_mov_b32_e32 v147, v4
	v_mov_b32_e32 v148, v4
	v_mov_b32_e32 v149, v4
	v_mov_b32_e32 v150, v4
	v_mov_b32_e32 v151, v4
	v_mov_b32_e32 v176, v4
	v_mov_b32_e32 v177, v4
	v_mov_b32_e32 v178, v4
	v_mov_b32_e32 v179, v4
	v_mov_b32_e32 v180, v4
	v_mov_b32_e32 v181, v4
	v_mov_b32_e32 v182, v4
	v_mov_b32_e32 v183, v4

; template <class Epi, class Sched, bool ALIGN_EPI = true>
; __device__ __forceinline__ void gemm_phase(PG8_LAS unsigned char* lds, const Gemm g, const Sched& S, const Epi& E, const int tid) {
;     ...
;         const char* nA = has_next ? (const char*)g.A + (size_t)nxt.pm * tstepA + (size_t)nxt.grp * g.gsA + (size_t)nxt.kt0 * kstep : cA;
;         const char* nB = has_next ? (const char*)g.Bt + (size_t)nxt.pn * tstepB + (size_t)nxt.grp * g.gsB + (size_t)nxt.kt0 * kstep : cB;
;     ...
; #pragma unroll
;         for (int a = 0; a < 2; ++a)
; #pragma unroll
;             for (int b = 0; b < 2; ++b)
; #pragma unroll
;                 for (int m = 0; m < 4; ++m)
; #pragma unroll
;                     for (int n = 0; n < 2; ++n) acc[a][b][m][n] = (f32x4){0.f, 0.f, 0.f, 0.f};
;         cur = nxt; cA = nA; cB = nB; ++ui;
.LBB0_1237:
	s_ashr_i32 s13, s12, 31
	s_lshl_b64 s[0:1], s[12:13], 20
	s_add_u32 s0, s81, s0
	s_addc_u32 s1, s82, s1
	s_and_b64 s[18:19], s[50:51], exec
	s_cselect_b32 s8, s1, s75
	s_cselect_b32 s11, s0, s74
	s_ashr_i32 s23, s22, 31
	s_lshl_b64 s[18:19], s[22:23], 20
	s_add_u32 s70, s83, s18
	s_addc_u32 s71, s84, s19
	s_and_b64 s[18:19], s[50:51], exec
	s_cselect_b32 s13, s71, s77
	s_cselect_b32 s18, s70, s76
	s_add_u32 s74, s74, 0x80080
	s_addc_u32 s75, s75, 0
	s_add_u32 s19, s76, 0x100
	v_mov_b32_e32 v12, 0
	s_addc_u32 s20, s77, 0
	s_mov_b32 s21, -2
	v_mov_b32_e32 v13, v12
	v_mov_b32_e32 v14, v12
	v_mov_b32_e32 v15, v12
	v_mov_b32_e32 v16, v12
	v_mov_b32_e32 v17, v12
	v_mov_b32_e32 v18, v12
	v_mov_b32_e32 v19, v12
	v_mov_b32_e32 v20, v12
	v_mov_b32_e32 v21, v12
	v_mov_b32_e32 v22, v12
	v_mov_b32_e32 v23, v12
	v_mov_b32_e32 v24, v12
	v_mov_b32_e32 v25, v12
	v_mov_b32_e32 v26, v12
	v_mov_b32_e32 v27, v12
	v_mov_b32_e32 v36, v12
	v_mov_b32_e32 v37, v12
	v_mov_b32_e32 v38, v12
	v_mov_b32_e32 v39, v12
	v_mov_b32_e32 v40, v12
	v_mov_b32_e32 v41, v12
	v_mov_b32_e32 v42, v12
	v_mov_b32_e32 v43, v12
	v_mov_b32_e32 v52, v12
	v_mov_b32_e32 v53, v12
	v_mov_b32_e32 v54, v12
	v_mov_b32_e32 v55, v12
	v_mov_b32_e32 v56, v12
	v_mov_b32_e32 v57, v12
	v_mov_b32_e32 v58, v12
	v_mov_b32_e32 v59, v12
	v_mov_b32_e32 v4, v12
	v_mov_b32_e32 v5, v12
	v_mov_b32_e32 v6, v12
	v_mov_b32_e32 v7, v12
	v_mov_b32_e32 v8, v12
	v_mov_b32_e32 v9, v12
	v_mov_b32_e32 v10, v12
	v_mov_b32_e32 v11, v12
	v_mov_b32_e32 v28, v12
	v_mov_b32_e32 v29, v12
	v_mov_b32_e32 v30, v12
	v_mov_b32_e32 v31, v12
	v_mov_b32_e32 v32, v12
	v_mov_b32_e32 v33, v12
	v_mov_b32_e32 v34, v12
	v_mov_b32_e32 v35, v12
	v_mov_b32_e32 v44, v12
	v_mov_b32_e32 v45, v12
	v_mov_b32_e32 v46, v12
	v_mov_b32_e32 v47, v12
	v_mov_b32_e32 v48, v12
	v_mov_b32_e32 v49, v12
	v_mov_b32_e32 v50, v12
	v_mov_b32_e32 v51, v12
	v_mov_b32_e32 v60, v12
	v_mov_b32_e32 v61, v12
	v_mov_b32_e32 v62, v12
	v_mov_b32_e32 v63, v12
	v_mov_b32_e32 v64, v12
	v_mov_b32_e32 v65, v12
	v_mov_b32_e32 v66, v12
	v_mov_b32_e32 v67, v12
	v_mov_b32_e32 v108, v12
	v_mov_b32_e32 v109, v12
	v_mov_b32_e32 v110, v12
	v_mov_b32_e32 v111, v12
	v_mov_b32_e32 v112, v12
	v_mov_b32_e32 v113, v12
	v_mov_b32_e32 v114, v12
	v_mov_b32_e32 v115, v12
	v_mov_b32_e32 v116, v12
	v_mov_b32_e32 v117, v12
	v_mov_b32_e32 v118, v12
	v_mov_b32_e32 v119, v12
	v_mov_b32_e32 v120, v12
	v_mov_b32_e32 v121, v12
	v_mov_b32_e32 v122, v12
	v_mov_b32_e32 v123, v12
	v_mov_b32_e32 v132, v12
	v_mov_b32_e32 v133, v12
	v_mov_b32_e32 v134, v12
	v_mov_b32_e32 v135, v12
	v_mov_b32_e32 v136, v12
	v_mov_b32_e32 v137, v12
	v_mov_b32_e32 v138, v12
	v_mov_b32_e32 v139, v12
	v_mov_b32_e32 v148, v12
	v_mov_b32_e32 v149, v12
	v_mov_b32_e32 v150, v12
	v_mov_b32_e32 v151, v12
	v_mov_b32_e32 v152, v12
	v_mov_b32_e32 v153, v12
	v_mov_b32_e32 v154, v12
	v_mov_b32_e32 v155, v12
	v_mov_b32_e32 v68, v12
	v_mov_b32_e32 v69, v12
	v_mov_b32_e32 v70, v12
	v_mov_b32_e32 v71, v12
	v_mov_b32_e32 v80, v12
	v_mov_b32_e32 v81, v12
	v_mov_b32_e32 v82, v12
	v_mov_b32_e32 v83, v12
	v_mov_b32_e32 v124, v12
	v_mov_b32_e32 v125, v12
	v_mov_b32_e32 v126, v12
	v_mov_b32_e32 v127, v12
	v_mov_b32_e32 v128, v12
	v_mov_b32_e32 v129, v12
	v_mov_b32_e32 v130, v12
	v_mov_b32_e32 v131, v12
	v_mov_b32_e32 v140, v12
	v_mov_b32_e32 v141, v12
	v_mov_b32_e32 v142, v12
	v_mov_b32_e32 v143, v12
	v_mov_b32_e32 v144, v12
	v_mov_b32_e32 v145, v12
	v_mov_b32_e32 v146, v12
	v_mov_b32_e32 v147, v12
	v_mov_b32_e32 v156, v12
	v_mov_b32_e32 v157, v12
	v_mov_b32_e32 v158, v12
	v_mov_b32_e32 v159, v12
	v_mov_b32_e32 v160, v12
	v_mov_b32_e32 v161, v12
	v_mov_b32_e32 v162, v12
	v_mov_b32_e32 v163, v12

; template <class Epi, class Sched, bool ALIGN_EPI = true>
; __device__ __forceinline__ void gemm_phase(PG8_LAS unsigned char* lds, const Gemm g, const Sched& S, const Epi& E, const int tid) {
;     ...
; #pragma unroll
;         for (int a = 0; a < 2; ++a)
; #pragma unroll
;             for (int b = 0; b < 2; ++b)
; #pragma unroll
;                 for (int m = 0; m < 4; ++m)
; #pragma unroll
;                     for (int n = 0; n < 2; ++n) acc[a][b][m][n] = (f32x4){0.f, 0.f, 0.f, 0.f};
;         cur = nxt; cA = nA; cB = nB; ++ui;
.LBB0_1413:
	s_add_i32 s45, s67, -2
	s_add_u32 s68, s12, 0x100
	v_mov_b32_e32 v4, 0
	s_addc_u32 s69, s13, 0
	s_mov_b32 s12, 0
	v_mov_b32_e32 v5, v4
	v_mov_b32_e32 v6, v4
	v_mov_b32_e32 v7, v4
	v_mov_b32_e32 v8, v4
	v_mov_b32_e32 v9, v4
	v_mov_b32_e32 v10, v4
	v_mov_b32_e32 v11, v4
	v_mov_b32_e32 v20, v4
	v_mov_b32_e32 v21, v4
	v_mov_b32_e32 v22, v4
	v_mov_b32_e32 v23, v4
	v_mov_b32_e32 v24, v4
	v_mov_b32_e32 v25, v4
	v_mov_b32_e32 v26, v4
	v_mov_b32_e32 v27, v4
	v_mov_b32_e32 v36, v4
	v_mov_b32_e32 v37, v4
	v_mov_b32_e32 v38, v4
	v_mov_b32_e32 v39, v4
	v_mov_b32_e32 v40, v4
	v_mov_b32_e32 v41, v4
	v_mov_b32_e32 v42, v4
	v_mov_b32_e32 v43, v4
	v_mov_b32_e32 v52, v4
	v_mov_b32_e32 v53, v4
	v_mov_b32_e32 v54, v4
	v_mov_b32_e32 v55, v4
	v_mov_b32_e32 v64, v4
	v_mov_b32_e32 v65, v4
	v_mov_b32_e32 v66, v4
	v_mov_b32_e32 v67, v4
	v_mov_b32_e32 v12, v4
	v_mov_b32_e32 v13, v4
	v_mov_b32_e32 v14, v4
	v_mov_b32_e32 v15, v4
	v_mov_b32_e32 v16, v4
	v_mov_b32_e32 v17, v4
	v_mov_b32_e32 v18, v4
	v_mov_b32_e32 v19, v4
	v_mov_b32_e32 v28, v4
	v_mov_b32_e32 v29, v4
	v_mov_b32_e32 v30, v4
	v_mov_b32_e32 v31, v4
	v_mov_b32_e32 v32, v4
	v_mov_b32_e32 v33, v4
	v_mov_b32_e32 v34, v4
	v_mov_b32_e32 v35, v4
	v_mov_b32_e32 v44, v4
	v_mov_b32_e32 v45, v4
	v_mov_b32_e32 v46, v4
	v_mov_b32_e32 v47, v4
	v_mov_b32_e32 v48, v4
	v_mov_b32_e32 v49, v4
	v_mov_b32_e32 v50, v4
	v_mov_b32_e32 v51, v4
	v_mov_b32_e32 v76, v4
	v_mov_b32_e32 v77, v4
	v_mov_b32_e32 v78, v4
	v_mov_b32_e32 v79, v4
	v_mov_b32_e32 v80, v4
	v_mov_b32_e32 v81, v4
	v_mov_b32_e32 v82, v4
	v_mov_b32_e32 v83, v4
	v_mov_b32_e32 v84, v4
	v_mov_b32_e32 v85, v4
	v_mov_b32_e32 v86, v4
	v_mov_b32_e32 v87, v4
	v_mov_b32_e32 v88, v4
	v_mov_b32_e32 v89, v4
	v_mov_b32_e32 v90, v4
	v_mov_b32_e32 v91, v4
	v_mov_b32_e32 v108, v4
	v_mov_b32_e32 v109, v4
	v_mov_b32_e32 v110, v4
	v_mov_b32_e32 v111, v4
	v_mov_b32_e32 v112, v4
	v_mov_b32_e32 v113, v4
	v_mov_b32_e32 v114, v4
	v_mov_b32_e32 v115, v4
	v_mov_b32_e32 v132, v4
	v_mov_b32_e32 v133, v4
	v_mov_b32_e32 v134, v4
	v_mov_b32_e32 v135, v4
	v_mov_b32_e32 v136, v4
	v_mov_b32_e32 v137, v4
	v_mov_b32_e32 v138, v4
	v_mov_b32_e32 v139, v4
	v_mov_b32_e32 v164, v4
	v_mov_b32_e32 v165, v4
	v_mov_b32_e32 v166, v4
	v_mov_b32_e32 v167, v4
	v_mov_b32_e32 v168, v4
	v_mov_b32_e32 v169, v4
	v_mov_b32_e32 v170, v4
	v_mov_b32_e32 v171, v4
	v_mov_b32_e32 v96, v4
	v_mov_b32_e32 v97, v4
	v_mov_b32_e32 v98, v4
	v_mov_b32_e32 v99, v4
	v_mov_b32_e32 v100, v4
	v_mov_b32_e32 v101, v4
	v_mov_b32_e32 v102, v4
	v_mov_b32_e32 v103, v4
	v_mov_b32_e32 v120, v4
	v_mov_b32_e32 v121, v4
	v_mov_b32_e32 v122, v4
	v_mov_b32_e32 v123, v4
	v_mov_b32_e32 v124, v4
	v_mov_b32_e32 v125, v4
	v_mov_b32_e32 v126, v4
	v_mov_b32_e32 v127, v4
	v_mov_b32_e32 v144, v4
	v_mov_b32_e32 v145, v4
	v_mov_b32_e32 v146, v4
	v_mov_b32_e32 v147, v4
	v_mov_b32_e32 v148, v4
	v_mov_b32_e32 v149, v4
	v_mov_b32_e32 v150, v4
	v_mov_b32_e32 v151, v4
	v_mov_b32_e32 v176, v4
	v_mov_b32_e32 v177, v4
	v_mov_b32_e32 v178, v4
	v_mov_b32_e32 v179, v4
	v_mov_b32_e32 v180, v4
	v_mov_b32_e32 v181, v4
	v_mov_b32_e32 v182, v4
	v_mov_b32_e32 v183, v4
	s_nop 0
	s_nop 0
	s_nop 0
	s_nop 0
